# placement census after grid sync: two dwordx4 sc1 loads instead of eight serialized dword loads; stacked
# speedup vs baseline: 1.0092x; 1.0092x over previous
; __device__ __forceinline__ int launder_s(int v) { asm volatile("" : "+s"(v)); return v; }
; __device__ __forceinline__ unsigned xb_ld(unsigned* p)              { return __hip_atomic_load(p, __ATOMIC_RELAXED, __HIP_MEMORY_SCOPE_AGENT); }
; #define ws (arg_ws())
; __global__ void __launch_bounds__(NTHR, 2) mk_fwd(Args a) {
;     ...
;     bool localok = fuse;
;     for (int g8 = 0; g8 < 8; ++g8) { const unsigned mk = (unsigned)__builtin_amdgcn_readfirstlane((int)xb_ld((unsigned*)(ws + WS_CTL) + 1024 + XB_MISMAP + g8)); localok = localok && mk != 0u && (mk & (mk - 1u)) == 0u; }
;     for (int l = 0; l < DEPTH; ++l) {
;         const int pb = launder_s(1 + 7 * l);
;         const float* modl = mod + (size_t)l * 8 * 6144;
;         if (INL(0) && !(fuse && l > 0)) {
;             const int m_lo = fuse ? (bx & 7) * SEQ + ((bx >> 3) * NWAVES + wave) * 16 : gw * 4, m_hi = fuse ? m_lo + 16 : M, m_st = fuse ? 4 : ngw * 4;
.LBB0_52:
	s_load_dwordx4 s[4:7], s[0:1], 0xa8
	v_mov_b32_e32 v0, 0xe000
	s_mul_i32 s95, s57, s56
	s_mov_b32 s71, 0
	s_mov_b32 s21, s71
	s_waitcnt lgkmcnt(0)
	s_mov_b64 s[8:9], s[4:5]
	s_cmp_eq_u32 s8, 0
	s_cselect_b64 s[4:5], -1, 0
	s_cmp_eq_u32 s9, 16
	s_cselect_b64 s[6:7], -1, 0
	s_cmpk_eq_i32 s56, 0x100
	s_cselect_b64 s[14:15], -1, 0
	s_cmpk_lg_i32 s56, 0x100
	s_cselect_b64 s[22:23], -1, 0
	s_and_b64 s[4:5], s[14:15], s[4:5]
	s_and_b64 s[12:13], s[4:5], s[6:7]
	s_movk_i32 s4, 0xa0
	s_xor_b64 s[10:11], s[12:13], -1
	s_ashr_i32 s5, s4, 31
	s_add_u32 s4, s0, s4
	s_addc_u32 s5, s1, s5
	s_load_dwordx2 s[4:5], s[4:5], 0x0
	v_writelane_b32 v253, s10, 2
	s_movk_i32 s8, 0xa0
	v_mov_b32_e32 v129, 0
	v_writelane_b32 v253, s11, 3
	s_waitcnt lgkmcnt(0)
	global_load_dwordx4 v[2:5], v0, s[4:5] offset:2256 sc1
	global_load_dwordx4 v[6:9], v0, s[4:5] offset:2272 sc1
	v_mov_b32_e32 v221, 1
	v_mov_b32_e32 v224, 0x50000
	v_mov_b32_e32 v225, 0xffffec00
	v_mov_b32_e32 v226, 0x1400
	s_movk_i32 s33, 0x1000
	s_mov_b32 s87, 0xffff0000
	s_mov_b32 s57, 0x800000
	s_mov_b32 s28, 0xed001000
	s_movk_i32 s84, 0x3000
	s_mov_b64 s[42:43], -1
	s_mov_b64 s[82:83], 0x1000
	s_mov_b64 s[36:37], 0
	s_mov_b32 s86, 0x3a800000
	s_mov_b32 s92, 0x358637bd
	s_mov_b64 s[52:53], 0x3000
	s_mov_b64 s[30:31], 0x3200000
	s_mov_b64 s[90:91], 0x80
	s_brev_b32 s89, 32
	s_mov_b32 s34, s71
	s_waitcnt vmcnt(0)
	v_readfirstlane_b32 s6, v2
	s_cmp_eq_u32 s6, 0
	s_cselect_b64 s[4:5], -1, 0
	s_add_i32 s7, s6, -1
	s_or_b64 s[4:5], s[10:11], s[4:5]
	s_and_b32 s6, s6, s7
	s_cmp_lg_u32 s6, 0
	s_cselect_b64 s[6:7], -1, 0
	s_ashr_i32 s9, s8, 31
	s_or_b64 s[4:5], s[4:5], s[6:7]
	s_add_u32 s6, s0, s8
	s_addc_u32 s7, s1, s9
	s_movk_i32 s8, 0xa0
	s_waitcnt vmcnt(0)
	v_readfirstlane_b32 s9, v3
	s_cmp_eq_u32 s9, 0
	s_cselect_b64 s[6:7], -1, 0
	s_add_i32 s10, s9, -1
	s_or_b64 s[4:5], s[4:5], s[6:7]
	s_and_b32 s6, s9, s10
	s_cmp_lg_u32 s6, 0
	s_cselect_b64 s[6:7], -1, 0
	s_ashr_i32 s9, s8, 31
	s_or_b64 s[4:5], s[4:5], s[6:7]
	s_add_u32 s6, s0, s8
	s_addc_u32 s7, s1, s9
	s_movk_i32 s8, 0xa0
	s_waitcnt vmcnt(0)
	v_readfirstlane_b32 s9, v4
	s_cmp_eq_u32 s9, 0
	s_cselect_b64 s[6:7], -1, 0
	s_add_i32 s10, s9, -1
	s_or_b64 s[4:5], s[4:5], s[6:7]
	s_and_b32 s6, s9, s10
	s_cmp_lg_u32 s6, 0
	s_cselect_b64 s[6:7], -1, 0
	s_ashr_i32 s9, s8, 31
	s_or_b64 s[4:5], s[4:5], s[6:7]
	s_add_u32 s6, s0, s8
	s_addc_u32 s7, s1, s9
	s_movk_i32 s8, 0xa0
	s_waitcnt vmcnt(0)
	v_readfirstlane_b32 s9, v5
	s_cmp_eq_u32 s9, 0
	s_cselect_b64 s[6:7], -1, 0
	s_add_i32 s10, s9, -1
	s_or_b64 s[4:5], s[4:5], s[6:7]
	s_and_b32 s6, s9, s10
	s_cmp_lg_u32 s6, 0
	s_cselect_b64 s[6:7], -1, 0
	s_ashr_i32 s9, s8, 31
	s_or_b64 s[4:5], s[4:5], s[6:7]
	s_add_u32 s6, s0, s8
	s_addc_u32 s7, s1, s9
	s_movk_i32 s8, 0xa0
	s_waitcnt vmcnt(0)
	v_readfirstlane_b32 s9, v6
	s_cmp_eq_u32 s9, 0
	s_cselect_b64 s[6:7], -1, 0
	s_add_i32 s10, s9, -1
	s_or_b64 s[4:5], s[4:5], s[6:7]
	s_and_b32 s6, s9, s10
	s_cmp_lg_u32 s6, 0
	s_cselect_b64 s[6:7], -1, 0
	s_ashr_i32 s9, s8, 31
	s_or_b64 s[4:5], s[4:5], s[6:7]
	s_add_u32 s6, s0, s8
	s_addc_u32 s7, s1, s9
	s_movk_i32 s8, 0xa0
	s_waitcnt vmcnt(0)
	v_readfirstlane_b32 s9, v7
	s_cmp_eq_u32 s9, 0
	s_cselect_b64 s[6:7], -1, 0
	s_add_i32 s10, s9, -1
	s_or_b64 s[4:5], s[4:5], s[6:7]
	s_and_b32 s6, s9, s10
	s_cmp_lg_u32 s6, 0
	s_cselect_b64 s[6:7], -1, 0
	s_ashr_i32 s9, s8, 31
	s_or_b64 s[4:5], s[4:5], s[6:7]
	s_add_u32 s6, s0, s8
	s_addc_u32 s7, s1, s9
	s_movk_i32 s8, 0xa0
	s_waitcnt vmcnt(0)
	v_readfirstlane_b32 s9, v8
	s_cmp_eq_u32 s9, 0
	s_cselect_b64 s[6:7], -1, 0
	s_add_i32 s10, s9, -1
	s_or_b64 s[4:5], s[4:5], s[6:7]
	s_and_b32 s6, s9, s10
	s_cmp_lg_u32 s6, 0
	s_cselect_b64 s[6:7], -1, 0
	s_ashr_i32 s9, s8, 31
	s_or_b64 s[4:5], s[4:5], s[6:7]
	s_add_u32 s6, s0, s8
	s_addc_u32 s7, s1, s9
	s_waitcnt vmcnt(0)
	v_readfirstlane_b32 s8, v9
	s_cmp_eq_u32 s8, 0
	s_cselect_b64 s[6:7], -1, 0
	s_add_i32 s9, s8, -1
	s_or_b64 s[4:5], s[4:5], s[6:7]
	s_and_b32 s6, s8, s9
	s_cmp_lg_u32 s6, 0
	s_cselect_b64 s[6:7], -1, 0
	s_or_b64 s[4:5], s[4:5], s[6:7]
	s_and_b32 s9, s24, 0xffffff8
	v_writelane_b32 v253, s4, 4
	s_lshl_b32 s8, s24, 12
	s_lshl_b32 s10, s26, 2
	v_writelane_b32 v253, s5, 5
	s_add_i32 s5, s25, s9
	s_and_b32 s4, s8, 0x7000
	s_lshl_b32 s5, s5, 4
	s_lshl_b32 s16, s56, 5
	s_add_i32 s6, s5, s4
	s_and_b64 s[4:5], s[12:13], exec
	s_cselect_b32 s20, 4, s16
	s_add_u32 s4, s54, 0x200
	s_addc_u32 s5, s55, 0
	v_writelane_b32 v253, s4, 6
	v_mbcnt_lo_u32_b32 v0, -1, 0
	s_nop 0
	v_writelane_b32 v253, s5, 7
	s_add_u32 s4, s54, 0x1000
	s_addc_u32 s5, s55, 0
	s_add_u32 s78, s54, 0x1100
	s_addc_u32 s79, s55, 0
	s_add_u32 s80, s54, 0x1200
	s_addc_u32 s81, s55, 0
	s_add_u32 s76, s54, 0x1300
	s_addc_u32 s77, s55, 0
	v_writelane_b32 v253, s4, 8
	s_cmp_eq_u32 s3, 15
	v_mbcnt_hi_u32_b32 v213, -1, v0
	v_writelane_b32 v253, s5, 9
	s_cselect_b64 s[4:5], -1, 0
	v_writelane_b32 v253, s4, 10
	s_cmp_eq_u32 s3, 14
	v_and_b32_e32 v0, 64, v213
	v_writelane_b32 v253, s5, 11
	s_cselect_b64 s[4:5], -1, 0
	v_writelane_b32 v253, s4, 12
	s_cmp_eq_u32 s3, 13
	v_xor_b32_e32 v252, 1, v213
	v_writelane_b32 v253, s5, 13
	s_cselect_b64 s[4:5], -1, 0
	v_writelane_b32 v253, s4, 14
	s_cmp_eq_u32 s3, 12
	v_xor_b32_e32 v227, 2, v213
	v_writelane_b32 v253, s5, 15
	s_cselect_b64 s[4:5], -1, 0
	v_writelane_b32 v253, s4, 16
	s_cmp_eq_u32 s3, 11
	v_xor_b32_e32 v216, 4, v213
	v_writelane_b32 v253, s5, 17
	s_cselect_b64 s[4:5], -1, 0
	v_writelane_b32 v253, s4, 18
	s_cmp_eq_u32 s3, 10
	v_xor_b32_e32 v217, 8, v213
	v_writelane_b32 v253, s5, 19
	s_cselect_b64 s[4:5], -1, 0
	v_writelane_b32 v253, s4, 20
	s_cmp_eq_u32 s3, 9
	v_xor_b32_e32 v218, 16, v213
	v_writelane_b32 v253, s5, 21
; __device__ __forceinline__ unsigned xb_ld(unsigned* p)              { return __hip_atomic_load(p, __ATOMIC_RELAXED, __HIP_MEMORY_SCOPE_AGENT); }
; #define x (arg_in(0))
;     __host__ __device__ bool next(int i, Unit& u) const {
;         const long L = (long)i * G + c; if (L >= nwg) return false;
;         int wgid = (int)L; { const int q = nwg / NXCD, r = nwg % NXCD, xcd = wgid % NXCD, off = wgid / NXCD; wgid = (xcd < r ? xcd * (q + 1) : r * (q + 1) + (xcd - r) * q) + off; }
;         const int nig = WGM * nN, gid = wgid / nig, fm = gid * WGM, gsz = (nM - fm) < WGM ? (nM - fm) : WGM;
;         u.pm = fm + ((wgid % nig) % gsz); u.pn = (wgid % nig) / gsz; return true;
; __device__ __forceinline__ void xcd_barrier_complete(unsigned* bar, unsigned x, unsigned& nloc, unsigned& nx) {
;     ...
;         sum = 0u; cnt = 0u; mine = 0u;
; #pragma unroll
;         for (unsigned j = 0; j < 16; ++j) { const unsigned c = xb_ld(&bar[XB_XCNT(j)]); sum += c; cnt += (c > 0u) ? 1u : 0u; mine = (j == x) ? c : mine; }
	s_cselect_b64 s[4:5], -1, 0
	v_writelane_b32 v253, s4, 22
	s_cmp_eq_u32 s3, 8
	v_xor_b32_e32 v219, 32, v213
	v_writelane_b32 v253, s5, 23
	s_cselect_b64 s[4:5], -1, 0
	v_writelane_b32 v253, s4, 24
	s_cmp_eq_u32 s3, 7
	v_add_u32_e32 v220, 64, v0
	v_writelane_b32 v253, s5, 25
	s_cselect_b64 s[4:5], -1, 0
	v_writelane_b32 v253, s4, 26
	s_cmp_eq_u32 s3, 6
	s_nop 0
	v_writelane_b32 v253, s5, 27
	s_cselect_b64 s[4:5], -1, 0
	v_writelane_b32 v253, s4, 28
	s_cmp_eq_u32 s3, 5
	s_nop 0
	v_writelane_b32 v253, s5, 29
	s_cselect_b64 s[4:5], -1, 0
	v_writelane_b32 v253, s4, 30
	s_cmp_eq_u32 s3, 4
	s_nop 0
	v_writelane_b32 v253, s5, 31
	s_cselect_b64 s[4:5], -1, 0
	v_writelane_b32 v253, s4, 32
	s_cmp_eq_u32 s3, 3
	s_nop 0
	v_writelane_b32 v253, s5, 33
	s_cselect_b64 s[4:5], -1, 0
	v_writelane_b32 v253, s4, 34
	s_cmp_eq_u32 s3, 2
	s_nop 0
	v_writelane_b32 v253, s5, 35
	s_cselect_b64 s[4:5], -1, 0
	v_writelane_b32 v253, s4, 36
	s_cmp_eq_u32 s3, 1
	s_nop 0
	v_writelane_b32 v253, s5, 37
	s_cselect_b64 s[4:5], -1, 0
	v_writelane_b32 v253, s4, 38
	s_cmp_eq_u32 s3, 0
	s_nop 0
	v_writelane_b32 v253, s5, 39
	s_cselect_b64 s[4:5], -1, 0
	s_lshl_b32 s3, s3, 8
	v_writelane_b32 v253, s4, 40
	s_add_u32 s3, s54, s3
	s_nop 0
	v_writelane_b32 v253, s5, 41
	s_addc_u32 s4, s55, 0
	s_add_u32 s8, s3, 0x1400
	s_addc_u32 s9, s4, 0
	v_writelane_b32 v253, s8, 42
	s_nop 1
	v_writelane_b32 v253, s9, 43
	s_add_u32 s8, s3, 0x2400
	s_addc_u32 s9, s4, 0
	v_writelane_b32 v253, s8, 44
	s_nop 1
	v_writelane_b32 v253, s9, 45
	s_add_u32 s8, s54, 0x3400
	s_addc_u32 s9, s55, 0
	v_writelane_b32 v253, s8, 46
	s_nop 1
	v_writelane_b32 v253, s9, 47
	s_add_u32 s8, s54, 0x3500
	s_addc_u32 s9, s55, 0
	v_writelane_b32 v253, s8, 48
	s_nop 1
	v_writelane_b32 v253, s9, 49
	s_add_u32 s8, s3, 0xb800
	s_addc_u32 s9, s4, 0
	v_writelane_b32 v253, s8, 50
	s_nop 1
	v_writelane_b32 v253, s9, 51
	s_add_u32 s8, s3, 0xc800
	s_addc_u32 s9, s4, 0
	v_writelane_b32 v253, s8, 52
	s_cmpk_lt_i32 s24, 0x500
	s_cselect_b64 s[4:5], -1, 0
	v_writelane_b32 v253, s9, 53
	v_writelane_b32 v253, s4, 54
	s_ashr_i32 s3, s24, 31
	s_and_b32 s7, s24, 7
	v_writelane_b32 v253, s5, 55
	s_nop 0
	v_readlane_b32 s4, v253, 0
	v_readlane_b32 s5, v253, 1
	v_writelane_b32 v253, s14, 56
	s_and_b64 s[4:5], s[4:5], s[14:15]
	s_nop 0
	v_writelane_b32 v253, s15, 57
	v_writelane_b32 v253, s4, 58
	s_nop 1
	v_writelane_b32 v253, s5, 59
	s_lshr_b32 s4, s3, 29
	s_add_i32 s4, s24, s4
	v_writelane_b32 v253, s7, 60
	s_lshl_b32 s5, s7, 6
	s_ashr_i32 s7, s4, 3
	s_and_b32 s4, s4, -8
	s_sub_i32 s8, s24, s4
	s_cmpk_lt_i32 s24, 0x200
	v_writelane_b32 v253, s5, 61
	s_cselect_b64 s[4:5], -1, 0
	s_lshl_b32 s9, s8, 6
	v_writelane_b32 v253, s4, 62
	s_cmpk_lt_i32 s24, 0xb00
	s_nop 0
	v_writelane_b32 v253, s5, 63
	s_cselect_b64 s[4:5], -1, 0
	v_writelane_b32 v254, s4, 0
	s_nop 1
	v_writelane_b32 v254, s5, 1
	s_and_b64 s[4:5], s[12:13], exec
	v_writelane_b32 v254, s10, 2
	s_cselect_b32 s14, s6, s10
	s_add_i32 s6, s6, 16
	v_writelane_b32 v254, s12, 3
	s_and_b64 s[4:5], s[12:13], exec
	s_cselect_b32 s27, s6, 0x8000
	s_cmp_ge_i32 s14, s27
	v_writelane_b32 v254, s13, 4
	s_cselect_b64 s[4:5], -1, 0
	v_writelane_b32 v254, s4, 5
	s_cmp_lt_i32 s8, 0
	s_movk_i32 s6, 0x161
	v_writelane_b32 v254, s5, 6
	s_movk_i32 s5, 0xa1
	s_cselect_b32 s5, s5, 0xa0
	s_mul_i32 s4, s8, 0x41
	s_mul_i32 s5, s8, s5
	s_cselect_b32 s6, s6, 0x160
	s_cselect_b32 s4, s4, s9
	s_mul_i32 s6, s8, s6
	s_add_i32 s5, s5, s7
	s_add_i32 s4, s4, s7
	s_add_i32 s6, s6, s7
	s_mul_hi_i32 s7, s5, 0x66666667
	s_lshr_b32 s8, s7, 31
	s_ashr_i32 s7, s7, 4
	s_add_i32 s7, s7, s8
	s_mul_hi_i32 s8, s6, 0x2e8ba2e9
	s_lshr_b32 s9, s8, 31
	s_ashr_i32 s8, s8, 4
	s_add_i32 s8, s8, s9
	s_ashr_i32 s9, s4, 31
	s_lshr_b32 s9, s9, 28
	s_add_i32 s9, s4, s9
	s_and_b32 s10, s9, 0xfff0
	s_sub_i32 s4, s4, s10
	s_mul_i32 s10, s7, 40
	s_sub_i32 s5, s5, s10
	s_mul_i32 s10, s8, 0x58
	s_sub_i32 s6, s6, s10
	s_bfe_i32 s10, s4, 0x80000
	s_bfe_u32 s10, s10, 0x2000d
	s_add_i32 s10, s4, s10
	s_and_b32 s11, s10, 0xfc
	s_sub_i32 s4, s4, s11
	s_bfe_i32 s11, s5, 0x80000
	s_bfe_u32 s11, s11, 0x2000d
	s_add_i32 s11, s5, s11
	s_and_b32 s12, s11, 0xfc
	s_sub_i32 s5, s5, s12
	s_bfe_i32 s12, s6, 0x80000
	s_bfe_u32 s12, s12, 0x2000d
	s_ashr_i32 s9, s9, 4
	s_bfe_i32 s10, s10, 0x80000
	s_add_i32 s12, s6, s12
	s_lshl_b32 s9, s9, 2
	s_sext_i32_i16 s10, s10
	s_sext_i32_i8 s4, s4
	s_and_b32 s13, s12, 0xfc
	s_add_i32 s18, s9, s4
	s_lshr_b32 s4, s10, 2
	s_sub_i32 s6, s6, s13
	s_sext_i32_i8 s13, s5
	s_bfe_i64 s[4:5], s[4:5], 0x100000
	s_bfe_i32 s12, s12, 0x80000
	s_lshl_b64 s[4:5], s[4:5], 19
	s_sext_i32_i16 s12, s12
	v_writelane_b32 v254, s4, 7
	s_bfe_i32 s11, s11, 0x80000
	s_lshl_b32 s8, s8, 2
	v_writelane_b32 v254, s5, 8
	s_ashr_i32 s4, s12, 2
	s_sext_i32_i16 s11, s11
	s_sext_i32_i8 s6, s6
	v_writelane_b32 v254, s4, 9
	s_lshr_b32 s4, s12, 2
	s_add_i32 s8, s8, s6
	s_bfe_i64 s[4:5], s[4:5], 0x100000
	s_ashr_i32 s6, s11, 2
	s_lshl_b32 s7, s7, 2
	v_writelane_b32 v254, s6, 10
	s_lshr_b32 s6, s11, 2
	s_lshl_b64 s[4:5], s[4:5], 19
	s_ashr_i32 s17, s10, 2
	s_add_i32 s10, s7, s13
	s_bfe_i64 s[6:7], s[6:7], 0x100000
	v_writelane_b32 v254, s4, 11
	s_ashr_i32 s19, s18, 31
	s_ashr_i32 s9, s8, 31
	v_writelane_b32 v254, s5, 12
	s_lshl_b64 s[4:5], s[6:7], 19
	v_writelane_b32 v254, s4, 13
	s_lshl_b64 s[6:7], s[18:19], 19
	s_ashr_i32 s15, s14, 31
	v_writelane_b32 v254, s5, 14
	v_writelane_b32 v254, s6, 15
	s_ashr_i32 s11, s10, 31
	s_lshl_b64 s[4:5], s[14:15], 11
	v_writelane_b32 v254, s7, 16
	s_mov_b32 s6, s8
	v_writelane_b32 v254, s6, 17
	s_nop 1
	v_writelane_b32 v254, s7, 18
	s_lshl_b64 s[6:7], s[8:9], 19
	v_writelane_b32 v254, s6, 19
	s_mov_b32 s9, 0x7060302
	s_nop 0
	v_writelane_b32 v254, s7, 20
	s_mov_b32 s6, s10
	v_writelane_b32 v254, s6, 21
	s_nop 1
	v_writelane_b32 v254, s7, 22
	s_lshl_b64 s[6:7], s[10:11], 19
	v_writelane_b32 v254, s6, 23
	s_add_u32 s4, s4, 0x16200000
	s_addc_u32 s5, s5, 0
	v_writelane_b32 v254, s7, 24
	v_writelane_b32 v254, s4, 25
	s_lshl_b32 s2, s2, 15
	s_lshl_b64 s[12:13], s[14:15], 12
	v_writelane_b32 v254, s5, 26
	s_load_dword s4, s[0:1], 0xc0
	s_lshl_b32 s97, s56, 15
	s_movk_i32 s5, 0x4000
	s_movk_i32 s6, 0x1400
	s_mov_b32 s7, 0x49800000
	s_waitcnt lgkmcnt(0)
; #define LAS __attribute__((address_space(3)))
; #define ws (arg_ws())
;     ...
;         { const float* wall = (const float*)(shm + LDS_WS);
; #pragma unroll
;           for (int w = 0; w < NW; ++w) { qa2 = fmaxf(qa2, wall[w * 128 + 0]); qb2 = fmaxf(qb2, wall[w * 128 + 1]); da = fminf(da, wall[w * 128 + 2]); db = fminf(db, wall[w * 128 + 3]); } }
; __global__ void __launch_bounds__(NTHR, 2) mk_fwd(Args a) {
;     ...
;                 const bool useq = G == 256; const int xg = bx & 7;
;                 unsigned* qcnt = (unsigned*)(ws + WS_CTL) + 15000 + (l * 8 + xg) * 64;
;                 volatile LAS unsigned* qw = (volatile LAS unsigned*)(ldsl + MISC_OFF) + 16;
	s_mul_i32 s95, s95, s4
	s_lshl_b32 s4, s25, 12
	s_add_i32 s2, s2, s4
	v_writelane_b32 v254, s2, 27
	s_movk_i32 s4, 0x7fff
	s_movk_i32 s10, 0xfff
	v_writelane_b32 v254, s3, 28
	s_mul_hi_i32 s2, s17, 0x160000
	v_writelane_b32 v254, s2, 29
	v_writelane_b32 v254, s17, 30
	s_mul_i32 s2, s17, 0x160000
	v_writelane_b32 v254, s2, 31
	s_mul_hi_i32 s2, s18, 0x160000
	v_writelane_b32 v254, s2, 32
	s_mov_b32 s2, s18
	v_writelane_b32 v254, s2, 33
	s_movk_i32 s11, 0x1600
	s_lshl_b64 s[60:61], s[20:21], 11
	v_writelane_b32 v254, s3, 34
	s_mul_i32 s2, s18, 0x160000
	v_writelane_b32 v254, s2, 35
	s_add_i32 s2, 0, 0x22020
	v_writelane_b32 v254, s2, 36
	s_add_i32 s2, 0, 0x22024
	v_writelane_b32 v254, s2, 37
	s_add_i32 s2, 0, 0x22040
	v_writelane_b32 v254, s2, 38
	s_add_i32 s2, 0, 0x10008
	v_writelane_b32 v254, s2, 39
	s_add_i32 s2, 0, 0x10208
	v_writelane_b32 v254, s2, 40
	s_add_i32 s2, 0, 0x10408
	v_writelane_b32 v254, s2, 41
	s_add_i32 s2, 0, 0x10608
	v_writelane_b32 v254, s2, 42
	s_add_i32 s2, 0, 0x10808
	v_writelane_b32 v254, s2, 43
	s_add_i32 s2, 0, 0x10a08
	v_writelane_b32 v254, s2, 44
	s_add_i32 s2, 0, 0x10c08
	v_writelane_b32 v254, s2, 45
	s_add_i32 s2, 0, 0x10e08
	v_writelane_b32 v254, s2, 46
	s_add_i32 s2, 0, 0x10200
	v_writelane_b32 v254, s2, 47
	s_add_i32 s2, 0, 0x10400
	v_writelane_b32 v254, s2, 48
	s_add_i32 s2, 0, 0x10600
	v_writelane_b32 v254, s2, 49
	s_add_i32 s2, 0, 0x10800
	v_writelane_b32 v254, s2, 50
	s_add_i32 s2, 0, 0x10a00
	v_writelane_b32 v254, s2, 51
	s_add_i32 s2, 0, 0x10c00
	v_writelane_b32 v254, s2, 52
	s_add_i32 s2, 0, 0x10e00
	v_writelane_b32 v254, s2, 53
	s_add_i32 s2, 0, 0x10004
	v_writelane_b32 v254, s2, 54
	s_add_i32 s2, 0, 0x10204
	v_writelane_b32 v254, s2, 55
	s_add_i32 s2, 0, 0x10404
	v_writelane_b32 v254, s2, 56
	s_add_i32 s2, 0, 0x10604
	v_writelane_b32 v254, s2, 57
	s_add_i32 s2, 0, 0x10804
	v_writelane_b32 v254, s2, 58
	s_add_i32 s2, 0, 0x10a04
	v_writelane_b32 v254, s2, 59
	s_add_i32 s2, 0, 0x10c04
	v_writelane_b32 v254, s2, 60
	s_add_i32 s2, 0, 0x10e04
	v_writelane_b32 v254, s2, 61
	s_add_i32 s2, 0, 0x1000c
	v_writelane_b32 v254, s2, 62
	s_add_i32 s2, 0, 0x1020c
	v_writelane_b32 v254, s2, 63
	s_add_i32 s2, 0, 0x1040c
	v_writelane_b32 v255, s2, 0
	s_add_i32 s2, 0, 0x1060c
	v_writelane_b32 v255, s2, 1
	s_add_i32 s2, 0, 0x1080c
	v_writelane_b32 v255, s2, 2
	s_add_i32 s2, 0, 0x10a0c
	v_writelane_b32 v255, s2, 3
	s_add_i32 s2, 0, 0x10c0c
	v_writelane_b32 v255, s2, 4
	s_add_i32 s2, 0, 0x10e0c
	v_writelane_b32 v255, s2, 5
	s_mov_b32 s2, s14
	v_writelane_b32 v255, s2, 6
	s_lshl_b64 s[68:69], s[20:21], 12
	s_nop 0
	v_writelane_b32 v255, s3, 7
	v_writelane_b32 v255, s12, 8
	s_mov_b32 s2, s20
	s_nop 0
	v_writelane_b32 v255, s13, 9
	v_writelane_b32 v255, s97, 10
	v_writelane_b32 v255, s22, 11
	s_nop 1
	v_writelane_b32 v255, s23, 12
	v_writelane_b32 v255, s2, 13
	s_nop 1
	v_writelane_b32 v255, s3, 14
	v_writelane_b32 v255, s27, 15
	v_writelane_b32 v255, s16, 16
	s_branch .LBB0_57
